# static priority 1 for waves 4-7 from the GLA chunk-state loop through attention and GLA outputs (no reset before the next GEMM phase)
# baseline (speedup 1.0000x reference)
; #define LAS __attribute__((address_space(3)))
; __global__ void __launch_bounds__(NWAVES * 64, 2) hymba_fwd(Args args) {
;     ...
;     { gla::GPre cur, nxt; int u = bid;
;       if (u < NCHUNK * 4) gla::load_pre<false>(cur, PROJ, args, WGT, STATE, u >> 2, u & 3);
;       for (; u < NCHUNK * 4; u += G) { const int un = u + G;
;         if (un < NCHUNK * 4) gla::load_pre<false>(nxt, PROJ, args, WGT, STATE, un >> 2, un & 3);
;         gla::g1_unit(cur, STATE, DEC, u >> 2, u & 3, (LAS char*)ldsl); cur = nxt; } }
.LBB0_196:
	v_cndmask_b32_e64 v32, 0, 1, s[0:1]
	v_cmp_ne_u32_e64 s[6:7], 1, v32
	s_add_u32 s4, s70, 0x1c000000
	s_addc_u32 s5, s71, 0
	v_writelane_b32 v255, s6, 15
	s_andn2_b64 vcc, exec, s[0:1]
	s_nop 0
	v_writelane_b32 v255, s7, 16
	s_cbranch_vccnz .LBB0_233
	s_add_i32 s0, s2, s74
	s_lshl_b32 s3, s0, 4
	s_lshl_b32 s15, s74, 4
	s_movk_i32 s25, 0x1a00
	s_mov_b32 s7, 0
	v_mov_b32_e32 v81, 0
	s_mov_b64 s[10:11], 0x1000
	s_movk_i32 s35, 0x1800
	s_movk_i32 s58, 0x110
	s_mov_b32 s59, 0xbfb8aa3b
	s_mov_b32 s14, 0x3f317218
	s_mov_b32 s24, 0x3db8aa3b
	s_mov_b32 s64, 0xffff0000
	s_movk_i32 s65, 0x7fff
	s_movk_i32 s72, 0x90
	v_mbcnt_hi_u32_b32 v125, -1, v124
	v_mov_b32_e32 v126, 0x900
	v_mov_b32_e32 v127, 0x1200
	v_mov_b32_e32 v128, 0x1b00
	s_mov_b32 s30, s2
	v_readfirstlane_b32 s98, v210
	s_cmpk_lt_u32 s98, 0x100
	s_cbranch_scc1 .Lprio_a
	s_setprio 1
.Lprio_a:
	s_waitcnt vmcnt(0)
	s_branch .LBB0_199
